# GEMM loops: ds_read base VGPRs precomputed per unit (no VALU left in K-loop) + saddr LDS-DMA form + no setprio; RET edits
# speedup vs baseline: 1.0129x; 1.0012x over previous
; #define PG8_STAGE(bufoff, gbase, voff) do { _Pragma("unroll") for (int _i = 0; _i < 2; ++_i) \
;         __builtin_amdgcn_global_load_lds((const unsigned*)((const char*)(gbase) + (voff)[_i]), (LAS unsigned*)(lds + (bufoff) + ldsw + _i * 8192), 16, 0, 0); } while (0)
; #define PG8_LDA(dst, b, h) do { _Pragma("unroll") for (int m = 0; m < 4; ++m) _Pragma("unroll") for (int k = 0; k < 2; ++k) dst[m][k] = *(const LAS bf16x8*)(lds + PG8_SA(b, h) + aoff + m * 2048 + k * 1024); } while (0)
; #define PG8_LDB(dst, b, h) do { _Pragma("unroll") for (int n = 0; n < 2; ++n) _Pragma("unroll") for (int k = 0; k < 2; ++k) dst[n][k] = *(const LAS bf16x8*)(lds + PG8_SB(b, h) + boff + n * 2048 + k * 1024); } while (0)
; #define PG8_MMA(ai, bj, At, Bt) do { __builtin_amdgcn_s_setprio(1); _Pragma("unroll") for (int m = 0; m < 4; ++m) _Pragma("unroll") for (int n = 0; n < 2; ++n) _Pragma("unroll") for (int k = 0; k < 2; ++k) \
;         acc[ai][bj][m][n] = __builtin_amdgcn_mfma_f32_16x16x32_bf16(Bt[n][k], At[m][k], acc[ai][bj][m][n], 0, 0, 0); __builtin_amdgcn_s_setprio(0); } while (0)
; #define PG8_WAIT_L(n) asm volatile("s_waitcnt lgkmcnt(" #n ")" ::: "memory")
; #define PG8_BAR __builtin_amdgcn_s_barrier()
; #define PG8_SCHED __builtin_amdgcn_sched_barrier(0)
; template <class Epi, class Sched>
; __device__ __forceinline__ void gemm_phase(LAS unsigned char* lds, const Gemm g, const Sched& S, const Epi& E) {
;     ...
;         for (int t = 0; t < nt; t += 2) {
;             const bool last = (t == nt - 2);
;             const char* a1 = cA + (size_t)(t + 1) * kstep;
;             const char* a2 = last ? nA : cA + (size_t)(t + 2) * kstep; const char* b2 = last ? nB : cB + (size_t)(t + 2) * kstep;
;             const char* a3 = a2 + kstep; const char* b3 = b2 + kstep;
;             PG8_LDB(B0, 0, 0); PG8_SCHED; PG8_LDA(At, 0, 0); PG8_STAGE(PG8_SA(1, 1), a1 + hstep, voffA);
;             PG8_WAIT_L(8); PG8_BAR; PG8_WAIT_L(0); PG8_MMA(0, 0, At, B0); PG8_BAR; PG8_SCHED;
;     ...
;         for (int a = 0; a < 2; ++a)
; #pragma unroll
;             for (int b = 0; b < 2; ++b)
; #pragma unroll
;                 for (int m = 0; m < 4; ++m)
; #pragma unroll
;                     for (int n = 0; n < 2; ++n) acc[a][b][m][n] = (f32x4){0.f, 0.f, 0.f, 0.f};
;         cur = nxt; cA = nA; cB = nB; ++ui;
.LBB0_230:
	v_readlane_b32 s24, v255, 3
	v_readlane_b32 s25, v255, 4
	s_andn2_b64 vcc, exec, s[24:25]
	s_cbranch_vccnz .LBB0_234
	v_add_u32_e32 v216, 0x10000, v191
	v_add_u32_e32 v217, 0x14000, v191
	v_add_u32_e32 v218, 0x18000, v191
	v_add_u32_e32 v219, 0x1c000, v191
	s_add_u32 s24, s26, 0x100
	s_addc_u32 s25, s27, 0
	s_add_u32 s26, s30, 0x80
	v_mov_b32_e32 v4, 0
	s_addc_u32 s27, s31, 0
	s_mov_b32 s29, 0
	v_mov_b32_e32 v5, v4
	v_mov_b32_e32 v6, v4
	v_mov_b32_e32 v7, v4
	v_mov_b32_e32 v12, v4
	v_mov_b32_e32 v13, v4
	v_mov_b32_e32 v14, v4
	v_mov_b32_e32 v15, v4
	v_mov_b32_e32 v20, v4
	v_mov_b32_e32 v21, v4
	v_mov_b32_e32 v22, v4
	v_mov_b32_e32 v23, v4
	v_mov_b32_e32 v28, v4
	v_mov_b32_e32 v29, v4
	v_mov_b32_e32 v30, v4
	v_mov_b32_e32 v31, v4
	v_mov_b32_e32 v36, v4
	v_mov_b32_e32 v37, v4
	v_mov_b32_e32 v38, v4
	v_mov_b32_e32 v39, v4
	v_mov_b32_e32 v44, v4
	v_mov_b32_e32 v45, v4
	v_mov_b32_e32 v46, v4
	v_mov_b32_e32 v47, v4
	v_mov_b32_e32 v52, v4
	v_mov_b32_e32 v53, v4
	v_mov_b32_e32 v54, v4
	v_mov_b32_e32 v55, v4
	v_mov_b32_e32 v60, v4
	v_mov_b32_e32 v61, v4
	v_mov_b32_e32 v62, v4
	v_mov_b32_e32 v63, v4
	v_mov_b32_e32 v0, v4
	v_mov_b32_e32 v1, v4
	v_mov_b32_e32 v2, v4
	v_mov_b32_e32 v3, v4
	v_mov_b32_e32 v8, v4
	v_mov_b32_e32 v9, v4
	v_mov_b32_e32 v10, v4
	v_mov_b32_e32 v11, v4
	v_mov_b32_e32 v16, v4
	v_mov_b32_e32 v17, v4
	v_mov_b32_e32 v18, v4
	v_mov_b32_e32 v19, v4
	v_mov_b32_e32 v24, v4
	v_mov_b32_e32 v25, v4
	v_mov_b32_e32 v26, v4
	v_mov_b32_e32 v27, v4
	v_mov_b32_e32 v32, v4
	v_mov_b32_e32 v33, v4
	v_mov_b32_e32 v34, v4
	v_mov_b32_e32 v35, v4
	v_mov_b32_e32 v40, v4
	v_mov_b32_e32 v41, v4
	v_mov_b32_e32 v42, v4
	v_mov_b32_e32 v43, v4
	v_mov_b32_e32 v48, v4
	v_mov_b32_e32 v49, v4
	v_mov_b32_e32 v50, v4
	v_mov_b32_e32 v51, v4
	v_mov_b32_e32 v56, v4
	v_mov_b32_e32 v57, v4
	v_mov_b32_e32 v58, v4
	v_mov_b32_e32 v59, v4
	v_mov_b32_e32 v68, v4
	v_mov_b32_e32 v69, v4
	v_mov_b32_e32 v70, v4
	v_mov_b32_e32 v71, v4
	v_mov_b32_e32 v76, v4
	v_mov_b32_e32 v77, v4
	v_mov_b32_e32 v78, v4
	v_mov_b32_e32 v79, v4
	v_mov_b32_e32 v84, v4
	v_mov_b32_e32 v85, v4
	v_mov_b32_e32 v86, v4
	v_mov_b32_e32 v87, v4
	v_mov_b32_e32 v92, v4
	v_mov_b32_e32 v93, v4
	v_mov_b32_e32 v94, v4
	v_mov_b32_e32 v95, v4
	v_mov_b32_e32 v100, v4
	v_mov_b32_e32 v101, v4
	v_mov_b32_e32 v102, v4
	v_mov_b32_e32 v103, v4
	v_mov_b32_e32 v108, v4
	v_mov_b32_e32 v109, v4
	v_mov_b32_e32 v110, v4
	v_mov_b32_e32 v111, v4
	v_mov_b32_e32 v116, v4
	v_mov_b32_e32 v117, v4
	v_mov_b32_e32 v118, v4
	v_mov_b32_e32 v119, v4
	v_mov_b32_e32 v124, v4
	v_mov_b32_e32 v125, v4
	v_mov_b32_e32 v126, v4
	v_mov_b32_e32 v127, v4
	v_mov_b32_e32 v64, v4
	v_mov_b32_e32 v65, v4
	v_mov_b32_e32 v66, v4
	v_mov_b32_e32 v67, v4
	v_mov_b32_e32 v72, v4
	v_mov_b32_e32 v73, v4
	v_mov_b32_e32 v74, v4
	v_mov_b32_e32 v75, v4
	v_mov_b32_e32 v80, v4
	v_mov_b32_e32 v81, v4
	v_mov_b32_e32 v82, v4
	v_mov_b32_e32 v83, v4
	v_mov_b32_e32 v88, v4
	v_mov_b32_e32 v89, v4
	v_mov_b32_e32 v90, v4
	v_mov_b32_e32 v91, v4
	v_mov_b32_e32 v96, v4
	v_mov_b32_e32 v97, v4
	v_mov_b32_e32 v98, v4
	v_mov_b32_e32 v99, v4
	v_mov_b32_e32 v104, v4
	v_mov_b32_e32 v105, v4
	v_mov_b32_e32 v106, v4
	v_mov_b32_e32 v107, v4
	v_mov_b32_e32 v112, v4
	v_mov_b32_e32 v113, v4
	v_mov_b32_e32 v114, v4
	v_mov_b32_e32 v115, v4
	v_mov_b32_e32 v120, v4
	v_mov_b32_e32 v121, v4
	v_mov_b32_e32 v122, v4
	v_mov_b32_e32 v123, v4
.LBB0_232:
	s_add_i32 s33, s29, 2
	s_add_u32 s30, s26, 0x80
	s_addc_u32 s31, s27, 0
	s_add_i32 s42, 0, 0x10000
	ds_read_b128 v[128:131], v216
	ds_read_b128 v[132:135], v216 offset:1024
	ds_read_b128 v[136:139], v216 offset:2048
	ds_read_b128 v[140:143], v216 offset:3072
	s_cmp_eq_u32 s76, s29
	s_cselect_b32 s31, s1, s31
	s_cselect_b32 s30, s0, s30
	s_cselect_b32 s35, s9, s25
	s_cselect_b32 s34, s8, s24
	s_add_i32 m0, s67, 0xc000
	ds_read_b128 v[144:147], v235
	ds_read_b128 v[148:151], v235 offset:1024
	ds_read_b128 v[152:155], v235 offset:2048
	ds_read_b128 v[156:159], v235 offset:3072
	ds_read_b128 v[160:163], v235 offset:4096
	ds_read_b128 v[164:167], v235 offset:5120
	ds_read_b128 v[168:171], v235 offset:6144
	ds_read_b128 v[172:175], v235 offset:7168
	global_load_lds_dwordx4 v194, s[26:27]
	s_add_i32 m0, s67, 0xe000
	s_nop 0
	global_load_lds_dwordx4 v192, s[26:27]
	s_waitcnt lgkmcnt(8)
	s_barrier
	s_waitcnt lgkmcnt(0)
	s_waitcnt lgkmcnt(0)
	v_mfma_f32_16x16x32_bf16 v[120:123], v[128:131], v[144:147], v[120:123]
	v_mfma_f32_16x16x32_bf16 v[112:115], v[136:139], v[144:147], v[112:115]
	v_mfma_f32_16x16x32_bf16 v[104:107], v[128:131], v[152:155], v[104:107]
	v_mfma_f32_16x16x32_bf16 v[96:99], v[136:139], v[152:155], v[96:99]
	v_mfma_f32_16x16x32_bf16 v[88:91], v[128:131], v[160:163], v[88:91]
	v_mfma_f32_16x16x32_bf16 v[80:83], v[136:139], v[160:163], v[80:83]
	v_mfma_f32_16x16x32_bf16 v[72:75], v[128:131], v[168:171], v[72:75]
	v_mfma_f32_16x16x32_bf16 v[64:67], v[136:139], v[168:171], v[64:67]
	v_mfma_f32_16x16x32_bf16 v[120:123], v[132:135], v[148:151], v[120:123]
	v_mfma_f32_16x16x32_bf16 v[112:115], v[140:143], v[148:151], v[112:115]
	v_mfma_f32_16x16x32_bf16 v[104:107], v[132:135], v[156:159], v[104:107]
	v_mfma_f32_16x16x32_bf16 v[96:99], v[140:143], v[156:159], v[96:99]
	v_mfma_f32_16x16x32_bf16 v[88:91], v[132:135], v[164:167], v[88:91]
	v_mfma_f32_16x16x32_bf16 v[80:83], v[140:143], v[164:167], v[80:83]
	v_mfma_f32_16x16x32_bf16 v[72:75], v[132:135], v[172:175], v[72:75]
	v_mfma_f32_16x16x32_bf16 v[64:67], v[140:143], v[172:175], v[64:67]
	s_barrier
; #define PG8_STAGE(bufoff, gbase, voff) do { _Pragma("unroll") for (int _i = 0; _i < 2; ++_i) \
;         __builtin_amdgcn_global_load_lds((const unsigned*)((const char*)(gbase) + (voff)[_i]), (LAS unsigned*)(lds + (bufoff) + ldsw + _i * 8192), 16, 0, 0); } while (0)
; #define PG8_LDA(dst, b, h) do { _Pragma("unroll") for (int m = 0; m < 4; ++m) _Pragma("unroll") for (int k = 0; k < 2; ++k) dst[m][k] = *(const LAS bf16x8*)(lds + PG8_SA(b, h) + aoff + m * 2048 + k * 1024); } while (0)
; #define PG8_LDB(dst, b, h) do { _Pragma("unroll") for (int n = 0; n < 2; ++n) _Pragma("unroll") for (int k = 0; k < 2; ++k) dst[n][k] = *(const LAS bf16x8*)(lds + PG8_SB(b, h) + boff + n * 2048 + k * 1024); } while (0)
; #define PG8_MMA(ai, bj, At, Bt) do { __builtin_amdgcn_s_setprio(1); _Pragma("unroll") for (int m = 0; m < 4; ++m) _Pragma("unroll") for (int n = 0; n < 2; ++n) _Pragma("unroll") for (int k = 0; k < 2; ++k) \
;         acc[ai][bj][m][n] = __builtin_amdgcn_mfma_f32_16x16x32_bf16(Bt[n][k], At[m][k], acc[ai][bj][m][n], 0, 0, 0); __builtin_amdgcn_s_setprio(0); } while (0)
; #define PG8_WAIT_V(n) asm volatile("s_waitcnt vmcnt(" #n ")" ::: "memory")
; #define PG8_WAIT_L(n) asm volatile("s_waitcnt lgkmcnt(" #n ")" ::: "memory")
; #define PG8_BAR __builtin_amdgcn_s_barrier()
; #define PG8_SCHED __builtin_amdgcn_sched_barrier(0)
; template <class Epi, class Sched>
; __device__ __forceinline__ void gemm_phase(LAS unsigned char* lds, const Gemm g, const Sched& S, const Epi& E) {
;     ...
;             PG8_LDB(B1, 0, 1); PG8_STAGE(PG8_SB(0, 0), b2, voffB);
;             PG8_BAR; PG8_WAIT_L(0); PG8_MMA(0, 1, At, B1); PG8_BAR;
;             PG8_LDA(At, 0, 1); PG8_STAGE(PG8_SA(0, 0), a2, voffA);
;             PG8_BAR; PG8_WAIT_L(0); PG8_MMA(1, 0, At, B0); PG8_BAR; PG8_SCHED;
;             PG8_STAGE(PG8_SB(0, 1), b2 + hstep, voffB);
;             PG8_WAIT_V(6); PG8_BAR; PG8_MMA(1, 1, At, B1); PG8_BAR;
;             PG8_LDB(B0, 1, 0); PG8_SCHED; PG8_LDA(At, 1, 0); PG8_STAGE(PG8_SA(0, 1), a2 + hstep, voffA);
	s_add_i32 s29, 0, 0x14000
	s_add_i32 s42, s42, s66
	s_mov_b32 m0, s42
	ds_read_b128 v[176:179], v217
	ds_read_b128 v[180:183], v217 offset:1024
	ds_read_b128 v[196:199], v217 offset:2048
	ds_read_b128 v[200:203], v217 offset:3072
	s_add_u32 s36, s34, 0x80
	s_addc_u32 s37, s35, 0
	global_load_lds_dwordx4 v188, s[34:35]
	s_add_i32 m0, s42, 0x2000
	s_nop 0
	global_load_lds_dwordx4 v184, s[34:35]
	s_barrier
	s_waitcnt lgkmcnt(0)
	s_waitcnt lgkmcnt(0)
	v_mfma_f32_16x16x32_bf16 v[124:127], v[176:179], v[144:147], v[124:127]
	v_mfma_f32_16x16x32_bf16 v[116:119], v[196:199], v[144:147], v[116:119]
	v_mfma_f32_16x16x32_bf16 v[108:111], v[176:179], v[152:155], v[108:111]
	v_mfma_f32_16x16x32_bf16 v[100:103], v[196:199], v[152:155], v[100:103]
	v_mfma_f32_16x16x32_bf16 v[92:95], v[176:179], v[160:163], v[92:95]
	v_mfma_f32_16x16x32_bf16 v[84:87], v[196:199], v[160:163], v[84:87]
	v_mfma_f32_16x16x32_bf16 v[76:79], v[176:179], v[168:171], v[76:79]
	v_mfma_f32_16x16x32_bf16 v[68:71], v[196:199], v[168:171], v[68:71]
	v_mfma_f32_16x16x32_bf16 v[124:127], v[180:183], v[148:151], v[124:127]
	v_mfma_f32_16x16x32_bf16 v[116:119], v[200:203], v[148:151], v[116:119]
	v_mfma_f32_16x16x32_bf16 v[108:111], v[180:183], v[156:159], v[108:111]
	v_mfma_f32_16x16x32_bf16 v[100:103], v[200:203], v[156:159], v[100:103]
	v_mfma_f32_16x16x32_bf16 v[92:95], v[180:183], v[164:167], v[92:95]
	v_mfma_f32_16x16x32_bf16 v[84:87], v[200:203], v[164:167], v[84:87]
	v_mfma_f32_16x16x32_bf16 v[76:79], v[180:183], v[172:175], v[76:79]
	v_mfma_f32_16x16x32_bf16 v[68:71], v[200:203], v[172:175], v[68:71]
	s_mov_b32 m0, s67
	s_barrier
	ds_read_b128 v[144:147], v235 offset:16384
	ds_read_b128 v[148:151], v235 offset:17408
	ds_read_b128 v[152:155], v235 offset:18432
	ds_read_b128 v[156:159], v235 offset:19456
	ds_read_b128 v[160:163], v235 offset:20480
	ds_read_b128 v[164:167], v235 offset:21504
	ds_read_b128 v[168:171], v235 offset:22528
	ds_read_b128 v[172:175], v235 offset:23552
	s_add_u32 s54, s30, 0x80
	s_addc_u32 s55, s31, 0
	global_load_lds_dwordx4 v188, s[30:31]
	s_mov_b32 m0, s68
	s_nop 0
	global_load_lds_dwordx4 v184, s[30:31]
	s_barrier
	s_waitcnt lgkmcnt(0)
	s_waitcnt lgkmcnt(0)
	v_mfma_f32_16x16x32_bf16 v[56:59], v[128:131], v[144:147], v[56:59]
	v_mfma_f32_16x16x32_bf16 v[48:51], v[136:139], v[144:147], v[48:51]
	v_mfma_f32_16x16x32_bf16 v[40:43], v[128:131], v[152:155], v[40:43]
	v_mfma_f32_16x16x32_bf16 v[32:35], v[136:139], v[152:155], v[32:35]
	v_mfma_f32_16x16x32_bf16 v[24:27], v[128:131], v[160:163], v[24:27]
	v_mfma_f32_16x16x32_bf16 v[16:19], v[136:139], v[160:163], v[16:19]
	v_mfma_f32_16x16x32_bf16 v[8:11], v[128:131], v[168:171], v[8:11]
	v_mfma_f32_16x16x32_bf16 v[0:3], v[136:139], v[168:171], v[0:3]
	v_mfma_f32_16x16x32_bf16 v[56:59], v[132:135], v[148:151], v[56:59]
	v_mfma_f32_16x16x32_bf16 v[48:51], v[140:143], v[148:151], v[48:51]
	v_mfma_f32_16x16x32_bf16 v[40:43], v[132:135], v[156:159], v[40:43]
	v_mfma_f32_16x16x32_bf16 v[32:35], v[140:143], v[156:159], v[32:35]
	v_mfma_f32_16x16x32_bf16 v[24:27], v[132:135], v[164:167], v[24:27]
	v_mfma_f32_16x16x32_bf16 v[16:19], v[140:143], v[164:167], v[16:19]
	v_mfma_f32_16x16x32_bf16 v[8:11], v[132:135], v[172:175], v[8:11]
	v_mfma_f32_16x16x32_bf16 v[0:3], v[140:143], v[172:175], v[0:3]
	s_barrier
	s_add_u32 s34, s34, s12
	s_addc_u32 s35, s35, s13
	s_add_u32 s84, s34, 0x80
	s_addc_u32 s85, s35, 0
	s_add_i32 s29, s29, s66
	s_mov_b32 m0, s29
	s_nop 0
	global_load_lds_dwordx4 v188, s[34:35]
	s_add_i32 m0, s29, 0x2000
	s_nop 0
	global_load_lds_dwordx4 v184, s[34:35]
	s_waitcnt vmcnt(6)
	s_barrier
	v_mfma_f32_16x16x32_bf16 v[60:63], v[176:179], v[144:147], v[60:63]
	v_mfma_f32_16x16x32_bf16 v[52:55], v[196:199], v[144:147], v[52:55]
	v_mfma_f32_16x16x32_bf16 v[44:47], v[176:179], v[152:155], v[44:47]
	v_mfma_f32_16x16x32_bf16 v[36:39], v[196:199], v[152:155], v[36:39]
	v_mfma_f32_16x16x32_bf16 v[28:31], v[176:179], v[160:163], v[28:31]
	v_mfma_f32_16x16x32_bf16 v[20:23], v[196:199], v[160:163], v[20:23]
	v_mfma_f32_16x16x32_bf16 v[12:15], v[176:179], v[168:171], v[12:15]
	v_mfma_f32_16x16x32_bf16 v[4:7], v[196:199], v[168:171], v[4:7]
	v_mfma_f32_16x16x32_bf16 v[60:63], v[180:183], v[148:151], v[60:63]
	v_mfma_f32_16x16x32_bf16 v[52:55], v[200:203], v[148:151], v[52:55]
	v_mfma_f32_16x16x32_bf16 v[44:47], v[180:183], v[156:159], v[44:47]
	v_mfma_f32_16x16x32_bf16 v[36:39], v[200:203], v[156:159], v[36:39]
	v_mfma_f32_16x16x32_bf16 v[28:31], v[180:183], v[164:167], v[28:31]
	v_mfma_f32_16x16x32_bf16 v[20:23], v[200:203], v[164:167], v[20:23]
	v_mfma_f32_16x16x32_bf16 v[12:15], v[180:183], v[172:175], v[12:15]
	v_mfma_f32_16x16x32_bf16 v[4:7], v[200:203], v[172:175], v[4:7]
	s_add_i32 s29, 0, 0x18000
	s_barrier
	ds_read_b128 v[128:131], v218
	ds_read_b128 v[132:135], v218 offset:1024
	ds_read_b128 v[136:139], v218 offset:2048
	ds_read_b128 v[140:143], v218 offset:3072
	s_add_u32 s30, s30, s12
	s_addc_u32 s31, s31, s13
	s_mov_b32 m0, s69
	ds_read_b128 v[144:147], v235 offset:32768
	ds_read_b128 v[148:151], v235 offset:33792
	ds_read_b128 v[152:155], v235 offset:34816
	ds_read_b128 v[156:159], v235 offset:35840
	ds_read_b128 v[160:163], v235 offset:36864
	ds_read_b128 v[164:167], v235 offset:37888
	ds_read_b128 v[168:171], v235 offset:38912
	ds_read_b128 v[172:175], v235 offset:39936
	global_load_lds_dwordx4 v188, s[30:31]
	s_mov_b32 m0, s70
	s_nop 0
	global_load_lds_dwordx4 v184, s[30:31]
	s_waitcnt lgkmcnt(8)
	s_barrier
; #define PG8_STAGE(bufoff, gbase, voff) do { _Pragma("unroll") for (int _i = 0; _i < 2; ++_i) \
;         __builtin_amdgcn_global_load_lds((const unsigned*)((const char*)(gbase) + (voff)[_i]), (LAS unsigned*)(lds + (bufoff) + ldsw + _i * 8192), 16, 0, 0); } while (0)
; #define PG8_LDA(dst, b, h) do { _Pragma("unroll") for (int m = 0; m < 4; ++m) _Pragma("unroll") for (int k = 0; k < 2; ++k) dst[m][k] = *(const LAS bf16x8*)(lds + PG8_SA(b, h) + aoff + m * 2048 + k * 1024); } while (0)
; #define PG8_LDB(dst, b, h) do { _Pragma("unroll") for (int n = 0; n < 2; ++n) _Pragma("unroll") for (int k = 0; k < 2; ++k) dst[n][k] = *(const LAS bf16x8*)(lds + PG8_SB(b, h) + boff + n * 2048 + k * 1024); } while (0)
; #define PG8_MMA(ai, bj, At, Bt) do { __builtin_amdgcn_s_setprio(1); _Pragma("unroll") for (int m = 0; m < 4; ++m) _Pragma("unroll") for (int n = 0; n < 2; ++n) _Pragma("unroll") for (int k = 0; k < 2; ++k) \
;         acc[ai][bj][m][n] = __builtin_amdgcn_mfma_f32_16x16x32_bf16(Bt[n][k], At[m][k], acc[ai][bj][m][n], 0, 0, 0); __builtin_amdgcn_s_setprio(0); } while (0)
; #define PG8_WAIT_V(n) asm volatile("s_waitcnt vmcnt(" #n ")" ::: "memory")
; #define PG8_WAIT_L(n) asm volatile("s_waitcnt lgkmcnt(" #n ")" ::: "memory")
; #define PG8_BAR __builtin_amdgcn_s_barrier()
; #define PG8_SCHED __builtin_amdgcn_sched_barrier(0)
; template <class Epi, class Sched>
; __device__ __forceinline__ void gemm_phase(LAS unsigned char* lds, const Gemm g, const Sched& S, const Epi& E) {
;     ...
;             PG8_WAIT_L(8); PG8_BAR; PG8_WAIT_L(0); PG8_MMA(0, 0, At, B0); PG8_BAR; PG8_SCHED;
;             PG8_LDB(B1, 1, 1); PG8_STAGE(PG8_SB(1, 0), b3, voffB);
;             PG8_BAR; PG8_WAIT_L(0); PG8_MMA(0, 1, At, B1); PG8_BAR;
;             PG8_LDA(At, 1, 1); PG8_STAGE(PG8_SA(1, 0), a3, voffA);
;             PG8_BAR; PG8_WAIT_L(0); PG8_MMA(1, 0, At, B0); PG8_BAR; PG8_SCHED;
;             PG8_STAGE(PG8_SB(1, 1), b3 + hstep, voffB);
;             PG8_WAIT_V(6); PG8_BAR; PG8_MMA(1, 1, At, B1); PG8_BAR;
;         }
	s_waitcnt lgkmcnt(0)
	s_waitcnt lgkmcnt(0)
	v_mfma_f32_16x16x32_bf16 v[120:123], v[128:131], v[144:147], v[120:123]
	v_mfma_f32_16x16x32_bf16 v[112:115], v[136:139], v[144:147], v[112:115]
	v_mfma_f32_16x16x32_bf16 v[104:107], v[128:131], v[152:155], v[104:107]
	v_mfma_f32_16x16x32_bf16 v[96:99], v[136:139], v[152:155], v[96:99]
	v_mfma_f32_16x16x32_bf16 v[88:91], v[128:131], v[160:163], v[88:91]
	v_mfma_f32_16x16x32_bf16 v[80:83], v[136:139], v[160:163], v[80:83]
	v_mfma_f32_16x16x32_bf16 v[72:75], v[128:131], v[168:171], v[72:75]
	v_mfma_f32_16x16x32_bf16 v[64:67], v[136:139], v[168:171], v[64:67]
	v_mfma_f32_16x16x32_bf16 v[120:123], v[132:135], v[148:151], v[120:123]
	v_mfma_f32_16x16x32_bf16 v[112:115], v[140:143], v[148:151], v[112:115]
	v_mfma_f32_16x16x32_bf16 v[104:107], v[132:135], v[156:159], v[104:107]
	v_mfma_f32_16x16x32_bf16 v[96:99], v[140:143], v[156:159], v[96:99]
	v_mfma_f32_16x16x32_bf16 v[88:91], v[132:135], v[164:167], v[88:91]
	v_mfma_f32_16x16x32_bf16 v[80:83], v[140:143], v[164:167], v[80:83]
	v_mfma_f32_16x16x32_bf16 v[72:75], v[132:135], v[172:175], v[72:75]
	v_mfma_f32_16x16x32_bf16 v[64:67], v[140:143], v[172:175], v[64:67]
	s_barrier
	s_add_i32 s30, 0, 0x1c000
	s_add_i32 s29, s29, s66
	s_mov_b32 m0, s29
	ds_read_b128 v[176:179], v219
	ds_read_b128 v[180:183], v219 offset:1024
	ds_read_b128 v[196:199], v219 offset:2048
	ds_read_b128 v[200:203], v219 offset:3072
	global_load_lds_dwordx4 v188, s[36:37]
	s_add_i32 m0, s29, 0x2000
	s_nop 0
	global_load_lds_dwordx4 v184, s[36:37]
	s_barrier
	s_waitcnt lgkmcnt(0)
	s_waitcnt lgkmcnt(0)
	v_mfma_f32_16x16x32_bf16 v[124:127], v[176:179], v[144:147], v[124:127]
	v_mfma_f32_16x16x32_bf16 v[116:119], v[196:199], v[144:147], v[116:119]
	v_mfma_f32_16x16x32_bf16 v[108:111], v[176:179], v[152:155], v[108:111]
	v_mfma_f32_16x16x32_bf16 v[100:103], v[196:199], v[152:155], v[100:103]
	v_mfma_f32_16x16x32_bf16 v[92:95], v[176:179], v[160:163], v[92:95]
	v_mfma_f32_16x16x32_bf16 v[84:87], v[196:199], v[160:163], v[84:87]
	v_mfma_f32_16x16x32_bf16 v[76:79], v[176:179], v[168:171], v[76:79]
	v_mfma_f32_16x16x32_bf16 v[68:71], v[196:199], v[168:171], v[68:71]
	v_mfma_f32_16x16x32_bf16 v[124:127], v[180:183], v[148:151], v[124:127]
	v_mfma_f32_16x16x32_bf16 v[116:119], v[200:203], v[148:151], v[116:119]
	v_mfma_f32_16x16x32_bf16 v[108:111], v[180:183], v[156:159], v[108:111]
	v_mfma_f32_16x16x32_bf16 v[100:103], v[200:203], v[156:159], v[100:103]
	v_mfma_f32_16x16x32_bf16 v[92:95], v[180:183], v[164:167], v[92:95]
	v_mfma_f32_16x16x32_bf16 v[84:87], v[200:203], v[164:167], v[84:87]
	v_mfma_f32_16x16x32_bf16 v[76:79], v[180:183], v[172:175], v[76:79]
	v_mfma_f32_16x16x32_bf16 v[68:71], v[200:203], v[172:175], v[68:71]
	s_mov_b32 m0, s18
	s_barrier
	ds_read_b128 v[144:147], v235 offset:49152
	ds_read_b128 v[148:151], v235 offset:50176
	ds_read_b128 v[152:155], v235 offset:51200
	ds_read_b128 v[156:159], v235 offset:52224
	ds_read_b128 v[160:163], v235 offset:53248
	ds_read_b128 v[164:167], v235 offset:54272
	ds_read_b128 v[168:171], v235 offset:55296
	ds_read_b128 v[172:175], v235 offset:56320
	global_load_lds_dwordx4 v188, s[54:55]
	s_mov_b32 m0, s75
	s_nop 0
	global_load_lds_dwordx4 v184, s[54:55]
	s_barrier
	s_waitcnt lgkmcnt(0)
	s_waitcnt lgkmcnt(0)
	v_mfma_f32_16x16x32_bf16 v[56:59], v[128:131], v[144:147], v[56:59]
	v_mfma_f32_16x16x32_bf16 v[48:51], v[136:139], v[144:147], v[48:51]
	v_mfma_f32_16x16x32_bf16 v[40:43], v[128:131], v[152:155], v[40:43]
	v_mfma_f32_16x16x32_bf16 v[32:35], v[136:139], v[152:155], v[32:35]
	v_mfma_f32_16x16x32_bf16 v[24:27], v[128:131], v[160:163], v[24:27]
	v_mfma_f32_16x16x32_bf16 v[16:19], v[136:139], v[160:163], v[16:19]
	v_mfma_f32_16x16x32_bf16 v[8:11], v[128:131], v[168:171], v[8:11]
	v_mfma_f32_16x16x32_bf16 v[0:3], v[136:139], v[168:171], v[0:3]
	v_mfma_f32_16x16x32_bf16 v[56:59], v[132:135], v[148:151], v[56:59]
	v_mfma_f32_16x16x32_bf16 v[48:51], v[140:143], v[148:151], v[48:51]
	v_mfma_f32_16x16x32_bf16 v[40:43], v[132:135], v[156:159], v[40:43]
	v_mfma_f32_16x16x32_bf16 v[32:35], v[140:143], v[156:159], v[32:35]
	v_mfma_f32_16x16x32_bf16 v[24:27], v[132:135], v[164:167], v[24:27]
	v_mfma_f32_16x16x32_bf16 v[16:19], v[140:143], v[164:167], v[16:19]
	v_mfma_f32_16x16x32_bf16 v[8:11], v[132:135], v[172:175], v[8:11]
	v_mfma_f32_16x16x32_bf16 v[0:3], v[140:143], v[172:175], v[0:3]
	s_barrier
	s_add_i32 s29, s30, s66
	s_mov_b32 m0, s29
	s_nop 0
	global_load_lds_dwordx4 v188, s[84:85]
	s_add_i32 m0, s29, 0x2000
	s_nop 0
	global_load_lds_dwordx4 v184, s[84:85]
	s_waitcnt vmcnt(6)
	s_barrier
	v_mfma_f32_16x16x32_bf16 v[60:63], v[176:179], v[144:147], v[60:63]
	v_mfma_f32_16x16x32_bf16 v[52:55], v[196:199], v[144:147], v[52:55]
	v_mfma_f32_16x16x32_bf16 v[44:47], v[176:179], v[152:155], v[44:47]
	v_mfma_f32_16x16x32_bf16 v[36:39], v[196:199], v[152:155], v[36:39]
	v_mfma_f32_16x16x32_bf16 v[28:31], v[176:179], v[160:163], v[28:31]
	v_mfma_f32_16x16x32_bf16 v[20:23], v[196:199], v[160:163], v[20:23]
	v_mfma_f32_16x16x32_bf16 v[12:15], v[176:179], v[168:171], v[12:15]
	v_mfma_f32_16x16x32_bf16 v[4:7], v[196:199], v[168:171], v[4:7]
	v_mfma_f32_16x16x32_bf16 v[60:63], v[180:183], v[148:151], v[60:63]
	v_mfma_f32_16x16x32_bf16 v[52:55], v[200:203], v[148:151], v[52:55]
	v_mfma_f32_16x16x32_bf16 v[44:47], v[180:183], v[156:159], v[44:47]
	v_mfma_f32_16x16x32_bf16 v[36:39], v[200:203], v[156:159], v[36:39]
	v_mfma_f32_16x16x32_bf16 v[28:31], v[180:183], v[164:167], v[28:31]
	v_mfma_f32_16x16x32_bf16 v[20:23], v[200:203], v[164:167], v[20:23]
	v_mfma_f32_16x16x32_bf16 v[12:15], v[180:183], v[172:175], v[12:15]
	v_mfma_f32_16x16x32_bf16 v[4:7], v[200:203], v[172:175], v[4:7]
	s_add_u32 s24, s24, 0x100
	s_addc_u32 s25, s25, 0
	s_add_u32 s26, s26, 0x100
	s_addc_u32 s27, s27, 0
	s_cmp_ge_i32 s33, s74
	s_mov_b32 s29, s33
	s_barrier
	s_cbranch_scc0 .LBB0_232
	s_mov_b32 s42, s82
	s_branch .LBB0_235

; #define PG8_STAGE(bufoff, gbase, voff) do { _Pragma("unroll") for (int _i = 0; _i < 2; ++_i) \
;         __builtin_amdgcn_global_load_lds((const unsigned*)((const char*)(gbase) + (voff)[_i]), (LAS unsigned*)(lds + (bufoff) + ldsw + _i * 8192), 16, 0, 0); } while (0)
; #define PG8_LDA(dst, b, h) do { _Pragma("unroll") for (int m = 0; m < 4; ++m) _Pragma("unroll") for (int k = 0; k < 2; ++k) dst[m][k] = *(const LAS bf16x8*)(lds + PG8_SA(b, h) + aoff + m * 2048 + k * 1024); } while (0)
; #define PG8_LDB(dst, b, h) do { _Pragma("unroll") for (int n = 0; n < 2; ++n) _Pragma("unroll") for (int k = 0; k < 2; ++k) dst[n][k] = *(const LAS bf16x8*)(lds + PG8_SB(b, h) + boff + n * 2048 + k * 1024); } while (0)
; #define PG8_MMA(ai, bj, At, Bt) do { __builtin_amdgcn_s_setprio(1); _Pragma("unroll") for (int m = 0; m < 4; ++m) _Pragma("unroll") for (int n = 0; n < 2; ++n) _Pragma("unroll") for (int k = 0; k < 2; ++k) \
;         acc[ai][bj][m][n] = __builtin_amdgcn_mfma_f32_16x16x32_bf16(Bt[n][k], At[m][k], acc[ai][bj][m][n], 0, 0, 0); __builtin_amdgcn_s_setprio(0); } while (0)
; #define PG8_WAIT_L(n) asm volatile("s_waitcnt lgkmcnt(" #n ")" ::: "memory")
; #define PG8_BAR __builtin_amdgcn_s_barrier()
; template <class Epi, class Sched>
; __device__ __forceinline__ void gemm_phase(LAS unsigned char* lds, const Gemm g, const Sched& S, const Epi& E) {
;     ...
;         for (int t = 0; t < nt; t += 2) {
;             const bool last = (t == nt - 2);
;             const char* a1 = cA + (size_t)(t + 1) * kstep;
;             const char* a2 = last ? nA : cA + (size_t)(t + 2) * kstep; const char* b2 = last ? nB : cB + (size_t)(t + 2) * kstep;
;             const char* a3 = a2 + kstep; const char* b3 = b2 + kstep;
;             PG8_LDB(B0, 0, 0); PG8_SCHED; PG8_LDA(At, 0, 0); PG8_STAGE(PG8_SA(1, 1), a1 + hstep, voffA);
;             PG8_WAIT_L(8); PG8_BAR; PG8_WAIT_L(0); PG8_MMA(0, 0, At, B0); PG8_BAR; PG8_SCHED;
;             PG8_LDB(B1, 0, 1); PG8_STAGE(PG8_SB(0, 0), b2, voffB);
;             PG8_BAR; PG8_WAIT_L(0); PG8_MMA(0, 1, At, B1); PG8_BAR;
;     ...
;         for (int a = 0; a < 2; ++a)
; #pragma unroll
;             for (int b = 0; b < 2; ++b)
; #pragma unroll
;                 for (int m = 0; m < 4; ++m)
; #pragma unroll
;                     for (int n = 0; n < 2; ++n) acc[a][b][m][n] = (f32x4){0.f, 0.f, 0.f, 0.f};
;         cur = nxt; cA = nA; cB = nB; ++ui;
.LBB0_337:
	v_readlane_b32 s0, v255, 3
	v_readlane_b32 s1, v255, 4
	s_andn2_b64 vcc, exec, s[0:1]
	s_cbranch_vccnz .LBB0_344
	v_add_u32_e32 v240, 0x10000, v214
	v_add_u32_e32 v241, 0x14000, v214
	v_add_u32_e32 v242, 0x18000, v214
	v_add_u32_e32 v243, 0x1c000, v214
	s_add_u32 s75, s28, 0x100
	s_addc_u32 s76, s29, 0
	s_add_u32 s0, s30, 0x80
	v_mov_b32_e32 v0, 0
	s_addc_u32 s1, s31, 0
	s_mov_b32 s4, 0
	v_mov_b32_e32 v1, v0
	v_mov_b32_e32 v2, v0
	v_mov_b32_e32 v3, v0
	v_mov_b32_e32 v8, v0
	v_mov_b32_e32 v9, v0
	v_mov_b32_e32 v10, v0
	v_mov_b32_e32 v11, v0
	v_mov_b32_e32 v16, v0
	v_mov_b32_e32 v17, v0
	v_mov_b32_e32 v18, v0
	v_mov_b32_e32 v19, v0
	v_mov_b32_e32 v24, v0
	v_mov_b32_e32 v25, v0
	v_mov_b32_e32 v26, v0
	v_mov_b32_e32 v27, v0
	v_mov_b32_e32 v32, v0
	v_mov_b32_e32 v33, v0
	v_mov_b32_e32 v34, v0
	v_mov_b32_e32 v35, v0
	v_mov_b32_e32 v40, v0
	v_mov_b32_e32 v41, v0
	v_mov_b32_e32 v42, v0
	v_mov_b32_e32 v43, v0
	v_mov_b32_e32 v48, v0
	v_mov_b32_e32 v49, v0
	v_mov_b32_e32 v50, v0
	v_mov_b32_e32 v51, v0
	v_mov_b32_e32 v56, v0
	v_mov_b32_e32 v57, v0
	v_mov_b32_e32 v58, v0
	v_mov_b32_e32 v59, v0
	v_mov_b32_e32 v4, v0
	v_mov_b32_e32 v5, v0
	v_mov_b32_e32 v6, v0
	v_mov_b32_e32 v7, v0
	v_mov_b32_e32 v12, v0
	v_mov_b32_e32 v13, v0
	v_mov_b32_e32 v14, v0
	v_mov_b32_e32 v15, v0
	v_mov_b32_e32 v20, v0
	v_mov_b32_e32 v21, v0
	v_mov_b32_e32 v22, v0
	v_mov_b32_e32 v23, v0
	v_mov_b32_e32 v28, v0
	v_mov_b32_e32 v29, v0
	v_mov_b32_e32 v30, v0
	v_mov_b32_e32 v31, v0
	v_mov_b32_e32 v36, v0
	v_mov_b32_e32 v37, v0
	v_mov_b32_e32 v38, v0
	v_mov_b32_e32 v39, v0
	v_mov_b32_e32 v44, v0
	v_mov_b32_e32 v45, v0
	v_mov_b32_e32 v46, v0
	v_mov_b32_e32 v47, v0
	v_mov_b32_e32 v52, v0
	v_mov_b32_e32 v53, v0
	v_mov_b32_e32 v54, v0
	v_mov_b32_e32 v55, v0
	v_mov_b32_e32 v60, v0
	v_mov_b32_e32 v61, v0
	v_mov_b32_e32 v62, v0
	v_mov_b32_e32 v63, v0
	v_mov_b32_e32 v68, v0
	v_mov_b32_e32 v69, v0
	v_mov_b32_e32 v70, v0
	v_mov_b32_e32 v71, v0
	v_mov_b32_e32 v76, v0
	v_mov_b32_e32 v77, v0
	v_mov_b32_e32 v78, v0
	v_mov_b32_e32 v79, v0
	v_mov_b32_e32 v84, v0
	v_mov_b32_e32 v85, v0
	v_mov_b32_e32 v86, v0
	v_mov_b32_e32 v87, v0
	v_mov_b32_e32 v92, v0
	v_mov_b32_e32 v93, v0
	v_mov_b32_e32 v94, v0
	v_mov_b32_e32 v95, v0
	v_mov_b32_e32 v100, v0
	v_mov_b32_e32 v101, v0
	v_mov_b32_e32 v102, v0
	v_mov_b32_e32 v103, v0
	v_mov_b32_e32 v108, v0
	v_mov_b32_e32 v109, v0
	v_mov_b32_e32 v110, v0
	v_mov_b32_e32 v111, v0
	v_mov_b32_e32 v116, v0
	v_mov_b32_e32 v117, v0
	v_mov_b32_e32 v118, v0
	v_mov_b32_e32 v119, v0
	v_mov_b32_e32 v124, v0
	v_mov_b32_e32 v125, v0
	v_mov_b32_e32 v126, v0
	v_mov_b32_e32 v127, v0
	v_mov_b32_e32 v64, v0
	v_mov_b32_e32 v65, v0
	v_mov_b32_e32 v66, v0
	v_mov_b32_e32 v67, v0
	v_mov_b32_e32 v72, v0
	v_mov_b32_e32 v73, v0
	v_mov_b32_e32 v74, v0
	v_mov_b32_e32 v75, v0
	v_mov_b32_e32 v80, v0
	v_mov_b32_e32 v81, v0
	v_mov_b32_e32 v82, v0
	v_mov_b32_e32 v83, v0
	v_mov_b32_e32 v88, v0
	v_mov_b32_e32 v89, v0
	v_mov_b32_e32 v90, v0
	v_mov_b32_e32 v91, v0
	v_mov_b32_e32 v96, v0
	v_mov_b32_e32 v97, v0
	v_mov_b32_e32 v98, v0
	v_mov_b32_e32 v99, v0
	v_mov_b32_e32 v104, v0
	v_mov_b32_e32 v105, v0
	v_mov_b32_e32 v106, v0
	v_mov_b32_e32 v107, v0
	v_mov_b32_e32 v112, v0
	v_mov_b32_e32 v113, v0
	v_mov_b32_e32 v114, v0
	v_mov_b32_e32 v115, v0
	v_mov_b32_e32 v120, v0
	v_mov_b32_e32 v121, v0
	v_mov_b32_e32 v122, v0
	v_mov_b32_e32 v123, v0
.LBB0_339:
	s_add_i32 s30, s4, 2
	s_add_u32 s28, s0, 0x80
	s_addc_u32 s5, s1, 0
	s_add_i32 s31, 0, 0x10000
	ds_read_b128 v[128:131], v240
	ds_read_b128 v[132:135], v240 offset:1024
	ds_read_b128 v[136:139], v240 offset:2048
	ds_read_b128 v[140:143], v240 offset:3072
	s_cmp_eq_u32 s66, s4
	s_cselect_b32 s4, s18, s28
	s_cselect_b32 s5, s19, s5
	s_cselect_b32 s29, s27, s76
	s_cselect_b32 s28, s26, s75
	s_add_i32 m0, s50, 0xc000
	ds_read_b128 v[144:147], v221
	ds_read_b128 v[148:151], v221 offset:1024
	ds_read_b128 v[152:155], v221 offset:2048
	ds_read_b128 v[156:159], v221 offset:3072
	ds_read_b128 v[160:163], v221 offset:4096
	ds_read_b128 v[164:167], v221 offset:5120
	ds_read_b128 v[168:171], v221 offset:6144
	ds_read_b128 v[172:175], v221 offset:7168
	global_load_lds_dwordx4 v200, s[0:1]
	s_add_i32 m0, s50, 0xe000
	s_nop 0
	global_load_lds_dwordx4 v198, s[0:1]
	s_waitcnt lgkmcnt(8)
	s_barrier
	s_waitcnt lgkmcnt(0)
	s_waitcnt lgkmcnt(0)
	v_mfma_f32_16x16x32_bf16 v[120:123], v[128:131], v[144:147], v[120:123]
	v_mfma_f32_16x16x32_bf16 v[112:115], v[136:139], v[144:147], v[112:115]
	v_mfma_f32_16x16x32_bf16 v[104:107], v[128:131], v[152:155], v[104:107]
	v_mfma_f32_16x16x32_bf16 v[96:99], v[136:139], v[152:155], v[96:99]
	v_mfma_f32_16x16x32_bf16 v[88:91], v[128:131], v[160:163], v[88:91]
	v_mfma_f32_16x16x32_bf16 v[80:83], v[136:139], v[160:163], v[80:83]
	v_mfma_f32_16x16x32_bf16 v[72:75], v[128:131], v[168:171], v[72:75]
	v_mfma_f32_16x16x32_bf16 v[64:67], v[136:139], v[168:171], v[64:67]
	v_mfma_f32_16x16x32_bf16 v[120:123], v[132:135], v[148:151], v[120:123]
	v_mfma_f32_16x16x32_bf16 v[112:115], v[140:143], v[148:151], v[112:115]
	v_mfma_f32_16x16x32_bf16 v[104:107], v[132:135], v[156:159], v[104:107]
	v_mfma_f32_16x16x32_bf16 v[96:99], v[140:143], v[156:159], v[96:99]
	v_mfma_f32_16x16x32_bf16 v[88:91], v[132:135], v[164:167], v[88:91]
	v_mfma_f32_16x16x32_bf16 v[80:83], v[140:143], v[164:167], v[80:83]
	v_mfma_f32_16x16x32_bf16 v[72:75], v[132:135], v[172:175], v[72:75]
	v_mfma_f32_16x16x32_bf16 v[64:67], v[140:143], v[172:175], v[64:67]
	s_barrier
	s_add_i32 s33, 0, 0x14000
	s_add_i32 s31, s31, s34
	s_mov_b32 m0, s31
	ds_read_b128 v[176:179], v241
	ds_read_b128 v[180:183], v241 offset:1024
	ds_read_b128 v[184:187], v241 offset:2048
	ds_read_b128 v[202:205], v241 offset:3072
	s_add_u32 s36, s28, 0x80
	s_addc_u32 s37, s29, 0
	global_load_lds_dwordx4 v192, s[28:29]
	s_add_i32 m0, s31, 0x2000
	s_nop 0
	global_load_lds_dwordx4 v194, s[28:29]
	s_barrier
; #define PG8_STAGE(bufoff, gbase, voff) do { _Pragma("unroll") for (int _i = 0; _i < 2; ++_i) \
;         __builtin_amdgcn_global_load_lds((const unsigned*)((const char*)(gbase) + (voff)[_i]), (LAS unsigned*)(lds + (bufoff) + ldsw + _i * 8192), 16, 0, 0); } while (0)
; #define PG8_LDA(dst, b, h) do { _Pragma("unroll") for (int m = 0; m < 4; ++m) _Pragma("unroll") for (int k = 0; k < 2; ++k) dst[m][k] = *(const LAS bf16x8*)(lds + PG8_SA(b, h) + aoff + m * 2048 + k * 1024); } while (0)
; #define PG8_LDB(dst, b, h) do { _Pragma("unroll") for (int n = 0; n < 2; ++n) _Pragma("unroll") for (int k = 0; k < 2; ++k) dst[n][k] = *(const LAS bf16x8*)(lds + PG8_SB(b, h) + boff + n * 2048 + k * 1024); } while (0)
; #define PG8_MMA(ai, bj, At, Bt) do { __builtin_amdgcn_s_setprio(1); _Pragma("unroll") for (int m = 0; m < 4; ++m) _Pragma("unroll") for (int n = 0; n < 2; ++n) _Pragma("unroll") for (int k = 0; k < 2; ++k) \
;         acc[ai][bj][m][n] = __builtin_amdgcn_mfma_f32_16x16x32_bf16(Bt[n][k], At[m][k], acc[ai][bj][m][n], 0, 0, 0); __builtin_amdgcn_s_setprio(0); } while (0)
; #define PG8_WAIT_V(n) asm volatile("s_waitcnt vmcnt(" #n ")" ::: "memory")
; #define PG8_WAIT_L(n) asm volatile("s_waitcnt lgkmcnt(" #n ")" ::: "memory")
; #define PG8_BAR __builtin_amdgcn_s_barrier()
; #define PG8_SCHED __builtin_amdgcn_sched_barrier(0)
; template <class Epi, class Sched>
; __device__ __forceinline__ void gemm_phase(LAS unsigned char* lds, const Gemm g, const Sched& S, const Epi& E) {
;     ...
;             PG8_BAR; PG8_WAIT_L(0); PG8_MMA(0, 1, At, B1); PG8_BAR;
;             PG8_LDA(At, 0, 1); PG8_STAGE(PG8_SA(0, 0), a2, voffA);
;             PG8_BAR; PG8_WAIT_L(0); PG8_MMA(1, 0, At, B0); PG8_BAR; PG8_SCHED;
;             PG8_STAGE(PG8_SB(0, 1), b2 + hstep, voffB);
;             PG8_WAIT_V(6); PG8_BAR; PG8_MMA(1, 1, At, B1); PG8_BAR;
;             PG8_LDB(B0, 1, 0); PG8_SCHED; PG8_LDA(At, 1, 0); PG8_STAGE(PG8_SA(0, 1), a2 + hstep, voffA);
	s_waitcnt lgkmcnt(0)
	s_waitcnt lgkmcnt(0)
	v_mfma_f32_16x16x32_bf16 v[124:127], v[176:179], v[144:147], v[124:127]
	v_mfma_f32_16x16x32_bf16 v[116:119], v[184:187], v[144:147], v[116:119]
	v_mfma_f32_16x16x32_bf16 v[108:111], v[176:179], v[152:155], v[108:111]
	v_mfma_f32_16x16x32_bf16 v[100:103], v[184:187], v[152:155], v[100:103]
	v_mfma_f32_16x16x32_bf16 v[92:95], v[176:179], v[160:163], v[92:95]
	v_mfma_f32_16x16x32_bf16 v[84:87], v[184:187], v[160:163], v[84:87]
	v_mfma_f32_16x16x32_bf16 v[76:79], v[176:179], v[168:171], v[76:79]
	v_mfma_f32_16x16x32_bf16 v[68:71], v[184:187], v[168:171], v[68:71]
	v_mfma_f32_16x16x32_bf16 v[124:127], v[180:183], v[148:151], v[124:127]
	v_mfma_f32_16x16x32_bf16 v[116:119], v[202:205], v[148:151], v[116:119]
	v_mfma_f32_16x16x32_bf16 v[108:111], v[180:183], v[156:159], v[108:111]
	v_mfma_f32_16x16x32_bf16 v[100:103], v[202:205], v[156:159], v[100:103]
	v_mfma_f32_16x16x32_bf16 v[92:95], v[180:183], v[164:167], v[92:95]
	v_mfma_f32_16x16x32_bf16 v[84:87], v[202:205], v[164:167], v[84:87]
	v_mfma_f32_16x16x32_bf16 v[76:79], v[180:183], v[172:175], v[76:79]
	v_mfma_f32_16x16x32_bf16 v[68:71], v[202:205], v[172:175], v[68:71]
	s_mov_b32 m0, s50
	s_barrier
	ds_read_b128 v[144:147], v221 offset:16384
	ds_read_b128 v[148:151], v221 offset:17408
	ds_read_b128 v[152:155], v221 offset:18432
	ds_read_b128 v[156:159], v221 offset:19456
	ds_read_b128 v[160:163], v221 offset:20480
	ds_read_b128 v[164:167], v221 offset:21504
	ds_read_b128 v[168:171], v221 offset:22528
	ds_read_b128 v[172:175], v221 offset:23552
	s_add_u32 s54, s4, 0x80
	s_addc_u32 s55, s5, 0
	global_load_lds_dwordx4 v192, s[4:5]
	s_mov_b32 m0, s51
	s_nop 0
	global_load_lds_dwordx4 v194, s[4:5]
	s_barrier
	s_waitcnt lgkmcnt(0)
	s_waitcnt lgkmcnt(0)
	v_mfma_f32_16x16x32_bf16 v[60:63], v[128:131], v[144:147], v[60:63]
	v_mfma_f32_16x16x32_bf16 v[52:55], v[136:139], v[144:147], v[52:55]
	v_mfma_f32_16x16x32_bf16 v[44:47], v[128:131], v[152:155], v[44:47]
	v_mfma_f32_16x16x32_bf16 v[36:39], v[136:139], v[152:155], v[36:39]
	v_mfma_f32_16x16x32_bf16 v[28:31], v[128:131], v[160:163], v[28:31]
	v_mfma_f32_16x16x32_bf16 v[20:23], v[136:139], v[160:163], v[20:23]
	v_mfma_f32_16x16x32_bf16 v[12:15], v[128:131], v[168:171], v[12:15]
	v_mfma_f32_16x16x32_bf16 v[4:7], v[136:139], v[168:171], v[4:7]
	v_mfma_f32_16x16x32_bf16 v[60:63], v[132:135], v[148:151], v[60:63]
	v_mfma_f32_16x16x32_bf16 v[52:55], v[140:143], v[148:151], v[52:55]
	v_mfma_f32_16x16x32_bf16 v[44:47], v[132:135], v[156:159], v[44:47]
	v_mfma_f32_16x16x32_bf16 v[36:39], v[140:143], v[156:159], v[36:39]
	v_mfma_f32_16x16x32_bf16 v[28:31], v[132:135], v[164:167], v[28:31]
	v_mfma_f32_16x16x32_bf16 v[20:23], v[140:143], v[164:167], v[20:23]
	v_mfma_f32_16x16x32_bf16 v[12:15], v[132:135], v[172:175], v[12:15]
	v_mfma_f32_16x16x32_bf16 v[4:7], v[140:143], v[172:175], v[4:7]
	s_barrier
	s_add_u32 s28, s28, s20
	s_addc_u32 s29, s29, s21
	s_add_u32 s84, s28, 0x80
	s_addc_u32 s85, s29, 0
	s_add_i32 s31, s33, s34
	s_mov_b32 m0, s31
	s_nop 0
	global_load_lds_dwordx4 v192, s[28:29]
	s_add_i32 m0, s31, 0x2000
	s_nop 0
	global_load_lds_dwordx4 v194, s[28:29]
	s_waitcnt vmcnt(6)
	s_barrier
	v_mfma_f32_16x16x32_bf16 v[56:59], v[176:179], v[144:147], v[56:59]
	v_mfma_f32_16x16x32_bf16 v[48:51], v[184:187], v[144:147], v[48:51]
	v_mfma_f32_16x16x32_bf16 v[40:43], v[176:179], v[152:155], v[40:43]
	v_mfma_f32_16x16x32_bf16 v[32:35], v[184:187], v[152:155], v[32:35]
	v_mfma_f32_16x16x32_bf16 v[24:27], v[176:179], v[160:163], v[24:27]
	v_mfma_f32_16x16x32_bf16 v[16:19], v[184:187], v[160:163], v[16:19]
	v_mfma_f32_16x16x32_bf16 v[8:11], v[176:179], v[168:171], v[8:11]
	v_mfma_f32_16x16x32_bf16 v[0:3], v[184:187], v[168:171], v[0:3]
	v_mfma_f32_16x16x32_bf16 v[56:59], v[180:183], v[148:151], v[56:59]
	v_mfma_f32_16x16x32_bf16 v[48:51], v[202:205], v[148:151], v[48:51]
	v_mfma_f32_16x16x32_bf16 v[40:43], v[180:183], v[156:159], v[40:43]
	v_mfma_f32_16x16x32_bf16 v[32:35], v[202:205], v[156:159], v[32:35]
	v_mfma_f32_16x16x32_bf16 v[24:27], v[180:183], v[164:167], v[24:27]
	v_mfma_f32_16x16x32_bf16 v[16:19], v[202:205], v[164:167], v[16:19]
	v_mfma_f32_16x16x32_bf16 v[8:11], v[180:183], v[172:175], v[8:11]
	v_mfma_f32_16x16x32_bf16 v[0:3], v[202:205], v[172:175], v[0:3]
	s_add_i32 s28, 0, 0x18000
	s_barrier
	ds_read_b128 v[128:131], v242
	ds_read_b128 v[132:135], v242 offset:1024
	ds_read_b128 v[136:139], v242 offset:2048
	ds_read_b128 v[140:143], v242 offset:3072
	s_add_u32 s4, s4, s20
	s_addc_u32 s5, s5, s21
	s_mov_b32 m0, s60
	ds_read_b128 v[144:147], v221 offset:32768
	ds_read_b128 v[148:151], v221 offset:33792
	ds_read_b128 v[152:155], v221 offset:34816
	ds_read_b128 v[156:159], v221 offset:35840
	ds_read_b128 v[160:163], v221 offset:36864
	ds_read_b128 v[164:167], v221 offset:37888
	ds_read_b128 v[168:171], v221 offset:38912
	ds_read_b128 v[172:175], v221 offset:39936
	global_load_lds_dwordx4 v192, s[4:5]
	s_mov_b32 m0, s61
	s_nop 0
	global_load_lds_dwordx4 v194, s[4:5]
	s_waitcnt lgkmcnt(8)
	s_barrier
; #define PG8_STAGE(bufoff, gbase, voff) do { _Pragma("unroll") for (int _i = 0; _i < 2; ++_i) \
;         __builtin_amdgcn_global_load_lds((const unsigned*)((const char*)(gbase) + (voff)[_i]), (LAS unsigned*)(lds + (bufoff) + ldsw + _i * 8192), 16, 0, 0); } while (0)
; #define PG8_LDA(dst, b, h) do { _Pragma("unroll") for (int m = 0; m < 4; ++m) _Pragma("unroll") for (int k = 0; k < 2; ++k) dst[m][k] = *(const LAS bf16x8*)(lds + PG8_SA(b, h) + aoff + m * 2048 + k * 1024); } while (0)
; #define PG8_LDB(dst, b, h) do { _Pragma("unroll") for (int n = 0; n < 2; ++n) _Pragma("unroll") for (int k = 0; k < 2; ++k) dst[n][k] = *(const LAS bf16x8*)(lds + PG8_SB(b, h) + boff + n * 2048 + k * 1024); } while (0)
; #define PG8_MMA(ai, bj, At, Bt) do { __builtin_amdgcn_s_setprio(1); _Pragma("unroll") for (int m = 0; m < 4; ++m) _Pragma("unroll") for (int n = 0; n < 2; ++n) _Pragma("unroll") for (int k = 0; k < 2; ++k) \
;         acc[ai][bj][m][n] = __builtin_amdgcn_mfma_f32_16x16x32_bf16(Bt[n][k], At[m][k], acc[ai][bj][m][n], 0, 0, 0); __builtin_amdgcn_s_setprio(0); } while (0)
; #define PG8_WAIT_V(n) asm volatile("s_waitcnt vmcnt(" #n ")" ::: "memory")
; #define PG8_WAIT_L(n) asm volatile("s_waitcnt lgkmcnt(" #n ")" ::: "memory")
; #define PG8_BAR __builtin_amdgcn_s_barrier()
; #define PG8_SCHED __builtin_amdgcn_sched_barrier(0)
; template <class Epi, class Sched>
; __device__ __forceinline__ void gemm_phase(LAS unsigned char* lds, const Gemm g, const Sched& S, const Epi& E) {
;     ...
;             PG8_WAIT_L(8); PG8_BAR; PG8_WAIT_L(0); PG8_MMA(0, 0, At, B0); PG8_BAR; PG8_SCHED;
;             PG8_LDB(B1, 1, 1); PG8_STAGE(PG8_SB(1, 0), b3, voffB);
;             PG8_BAR; PG8_WAIT_L(0); PG8_MMA(0, 1, At, B1); PG8_BAR;
;             PG8_LDA(At, 1, 1); PG8_STAGE(PG8_SA(1, 0), a3, voffA);
;             PG8_BAR; PG8_WAIT_L(0); PG8_MMA(1, 0, At, B0); PG8_BAR; PG8_SCHED;
;             PG8_STAGE(PG8_SB(1, 1), b3 + hstep, voffB);
;             PG8_WAIT_V(6); PG8_BAR; PG8_MMA(1, 1, At, B1); PG8_BAR;
;         }
	s_waitcnt lgkmcnt(0)
	s_waitcnt lgkmcnt(0)
	v_mfma_f32_16x16x32_bf16 v[120:123], v[128:131], v[144:147], v[120:123]
	v_mfma_f32_16x16x32_bf16 v[112:115], v[136:139], v[144:147], v[112:115]
	v_mfma_f32_16x16x32_bf16 v[104:107], v[128:131], v[152:155], v[104:107]
	v_mfma_f32_16x16x32_bf16 v[96:99], v[136:139], v[152:155], v[96:99]
	v_mfma_f32_16x16x32_bf16 v[88:91], v[128:131], v[160:163], v[88:91]
	v_mfma_f32_16x16x32_bf16 v[80:83], v[136:139], v[160:163], v[80:83]
	v_mfma_f32_16x16x32_bf16 v[72:75], v[128:131], v[168:171], v[72:75]
	v_mfma_f32_16x16x32_bf16 v[64:67], v[136:139], v[168:171], v[64:67]
	v_mfma_f32_16x16x32_bf16 v[120:123], v[132:135], v[148:151], v[120:123]
	v_mfma_f32_16x16x32_bf16 v[112:115], v[140:143], v[148:151], v[112:115]
	v_mfma_f32_16x16x32_bf16 v[104:107], v[132:135], v[156:159], v[104:107]
	v_mfma_f32_16x16x32_bf16 v[96:99], v[140:143], v[156:159], v[96:99]
	v_mfma_f32_16x16x32_bf16 v[88:91], v[132:135], v[164:167], v[88:91]
	v_mfma_f32_16x16x32_bf16 v[80:83], v[140:143], v[164:167], v[80:83]
	v_mfma_f32_16x16x32_bf16 v[72:75], v[132:135], v[172:175], v[72:75]
	v_mfma_f32_16x16x32_bf16 v[64:67], v[140:143], v[172:175], v[64:67]
	s_barrier
	s_add_i32 s4, 0, 0x1c000
	s_add_i32 s5, s28, s34
	s_mov_b32 m0, s5
	ds_read_b128 v[176:179], v243
	ds_read_b128 v[180:183], v243 offset:1024
	ds_read_b128 v[184:187], v243 offset:2048
	ds_read_b128 v[202:205], v243 offset:3072
	global_load_lds_dwordx4 v192, s[36:37]
	s_add_i32 m0, s5, 0x2000
	s_nop 0
	global_load_lds_dwordx4 v194, s[36:37]
	s_barrier
	s_waitcnt lgkmcnt(0)
	s_waitcnt lgkmcnt(0)
	v_mfma_f32_16x16x32_bf16 v[124:127], v[176:179], v[144:147], v[124:127]
	v_mfma_f32_16x16x32_bf16 v[116:119], v[184:187], v[144:147], v[116:119]
	v_mfma_f32_16x16x32_bf16 v[108:111], v[176:179], v[152:155], v[108:111]
	v_mfma_f32_16x16x32_bf16 v[100:103], v[184:187], v[152:155], v[100:103]
	v_mfma_f32_16x16x32_bf16 v[92:95], v[176:179], v[160:163], v[92:95]
	v_mfma_f32_16x16x32_bf16 v[84:87], v[184:187], v[160:163], v[84:87]
	v_mfma_f32_16x16x32_bf16 v[76:79], v[176:179], v[168:171], v[76:79]
	v_mfma_f32_16x16x32_bf16 v[68:71], v[184:187], v[168:171], v[68:71]
	v_mfma_f32_16x16x32_bf16 v[124:127], v[180:183], v[148:151], v[124:127]
	v_mfma_f32_16x16x32_bf16 v[116:119], v[202:205], v[148:151], v[116:119]
	v_mfma_f32_16x16x32_bf16 v[108:111], v[180:183], v[156:159], v[108:111]
	v_mfma_f32_16x16x32_bf16 v[100:103], v[202:205], v[156:159], v[100:103]
	v_mfma_f32_16x16x32_bf16 v[92:95], v[180:183], v[164:167], v[92:95]
	v_mfma_f32_16x16x32_bf16 v[84:87], v[202:205], v[164:167], v[84:87]
	v_mfma_f32_16x16x32_bf16 v[76:79], v[180:183], v[172:175], v[76:79]
	v_mfma_f32_16x16x32_bf16 v[68:71], v[202:205], v[172:175], v[68:71]
	s_mov_b32 m0, s62
	s_barrier
	ds_read_b128 v[144:147], v221 offset:49152
	ds_read_b128 v[148:151], v221 offset:50176
	ds_read_b128 v[152:155], v221 offset:51200
	ds_read_b128 v[156:159], v221 offset:52224
	ds_read_b128 v[160:163], v221 offset:53248
	ds_read_b128 v[164:167], v221 offset:54272
	ds_read_b128 v[168:171], v221 offset:55296
	ds_read_b128 v[172:175], v221 offset:56320
	global_load_lds_dwordx4 v192, s[54:55]
	s_mov_b32 m0, s63
	s_nop 0
	global_load_lds_dwordx4 v194, s[54:55]
	s_barrier
	s_waitcnt lgkmcnt(0)
	s_waitcnt lgkmcnt(0)
	v_mfma_f32_16x16x32_bf16 v[60:63], v[128:131], v[144:147], v[60:63]
	v_mfma_f32_16x16x32_bf16 v[52:55], v[136:139], v[144:147], v[52:55]
	v_mfma_f32_16x16x32_bf16 v[44:47], v[128:131], v[152:155], v[44:47]
	v_mfma_f32_16x16x32_bf16 v[36:39], v[136:139], v[152:155], v[36:39]
	v_mfma_f32_16x16x32_bf16 v[28:31], v[128:131], v[160:163], v[28:31]
	v_mfma_f32_16x16x32_bf16 v[20:23], v[136:139], v[160:163], v[20:23]
	v_mfma_f32_16x16x32_bf16 v[12:15], v[128:131], v[168:171], v[12:15]
	v_mfma_f32_16x16x32_bf16 v[4:7], v[136:139], v[168:171], v[4:7]
	v_mfma_f32_16x16x32_bf16 v[60:63], v[132:135], v[148:151], v[60:63]
	v_mfma_f32_16x16x32_bf16 v[52:55], v[140:143], v[148:151], v[52:55]
	v_mfma_f32_16x16x32_bf16 v[44:47], v[132:135], v[156:159], v[44:47]
	v_mfma_f32_16x16x32_bf16 v[36:39], v[140:143], v[156:159], v[36:39]
	v_mfma_f32_16x16x32_bf16 v[28:31], v[132:135], v[164:167], v[28:31]
	v_mfma_f32_16x16x32_bf16 v[20:23], v[140:143], v[164:167], v[20:23]
	v_mfma_f32_16x16x32_bf16 v[12:15], v[132:135], v[172:175], v[12:15]
	v_mfma_f32_16x16x32_bf16 v[4:7], v[140:143], v[172:175], v[4:7]
	s_barrier
	s_add_i32 s4, s4, s34
	s_mov_b32 m0, s4
	s_nop 0
	global_load_lds_dwordx4 v192, s[84:85]
	s_add_i32 m0, s4, 0x2000
	s_nop 0
	global_load_lds_dwordx4 v194, s[84:85]
	s_waitcnt vmcnt(6)
	s_barrier
	v_mfma_f32_16x16x32_bf16 v[56:59], v[176:179], v[144:147], v[56:59]
	v_mfma_f32_16x16x32_bf16 v[48:51], v[184:187], v[144:147], v[48:51]
	v_mfma_f32_16x16x32_bf16 v[40:43], v[176:179], v[152:155], v[40:43]
	v_mfma_f32_16x16x32_bf16 v[32:35], v[184:187], v[152:155], v[32:35]
	v_mfma_f32_16x16x32_bf16 v[24:27], v[176:179], v[160:163], v[24:27]
	v_mfma_f32_16x16x32_bf16 v[16:19], v[184:187], v[160:163], v[16:19]
	v_mfma_f32_16x16x32_bf16 v[8:11], v[176:179], v[168:171], v[8:11]
	v_mfma_f32_16x16x32_bf16 v[0:3], v[184:187], v[168:171], v[0:3]
	v_mfma_f32_16x16x32_bf16 v[56:59], v[180:183], v[148:151], v[56:59]
	v_mfma_f32_16x16x32_bf16 v[48:51], v[202:205], v[148:151], v[48:51]
	v_mfma_f32_16x16x32_bf16 v[40:43], v[180:183], v[156:159], v[40:43]
	v_mfma_f32_16x16x32_bf16 v[32:35], v[202:205], v[156:159], v[32:35]
	v_mfma_f32_16x16x32_bf16 v[24:27], v[180:183], v[164:167], v[24:27]
	v_mfma_f32_16x16x32_bf16 v[16:19], v[202:205], v[164:167], v[16:19]
	v_mfma_f32_16x16x32_bf16 v[8:11], v[180:183], v[172:175], v[8:11]
	v_mfma_f32_16x16x32_bf16 v[0:3], v[202:205], v[172:175], v[0:3]
	s_add_u32 s75, s75, 0x100
	s_addc_u32 s76, s76, 0
	s_add_u32 s0, s0, 0x100
	s_addc_u32 s1, s1, 0
	s_cmp_ge_i32 s30, s13
	s_mov_b32 s4, s30
	s_barrier
	s_cbranch_scc0 .LBB0_339
	s_mov_b32 s33, 0x200000
	s_cmp_lt_i32 s15, 2
	s_cbranch_scc1 .LBB0_345
